# router reduction: lane^16 / lane^32 stages via v_permlane16_swap / v_permlane32_swap instead of ds_bpermute (on top of v38)
# baseline (speedup 1.0000x reference)
; __global__ void __launch_bounds__(NTHR) fwd_megakernel(Params p) {
;     ...
;       for (int e = 0; e < 16; ++e) {
;         float a4[4] = {0.f, 0.f, 0.f, 0.f};
; #pragma unroll
;         for (int i = 0; i < 4; ++i) {
;           const float4 w = *(const float4*)(wr + e * 1028 + i * 256 + lane * 4);
; #pragma unroll
;           for (int rr = 0; rr < 4; ++rr)
;             a4[rr] += yv[rr][i * 4] * w.x + yv[rr][i * 4 + 1] * w.y + yv[rr][i * 4 + 2] * w.z + yv[rr][i * 4 + 3] * w.w;
;         }
.LBB0_1023:
.Lrt_loop:
	v_add_u32_e32 v1, s14, v102
	ds_read_b128 v[20:23], v1
	ds_read_b128 v[32:35], v1 offset:1024
	ds_read_b128 v[130:133], v1 offset:2048
	ds_read_b128 v[134:137], v1 offset:3072
	s_waitcnt lgkmcnt(3)
	v_mul_f32_e32 v1, v21, v118
	v_mul_f32_e32 v5, v21, v121
	v_mul_f32_e32 v100, v21, v61
	v_mul_f32_e32 v101, v21, v65
	s_waitcnt lgkmcnt(2)
	v_mul_f32_e32 v126, v33, v67
	v_mul_f32_e32 v127, v33, v95
	v_mul_f32_e32 v129, v33, v125
	v_mul_f32_e32 v138, v33, v57
	s_waitcnt lgkmcnt(0)
	v_mov_b32_e32 v7, v134
	v_mov_b32_e32 v134, v131
	v_fmac_f32_e32 v1, v20, v117
	v_fmac_f32_e32 v5, v20, v91
	v_fmac_f32_e32 v100, v20, v60
	v_fmac_f32_e32 v101, v20, v64
	v_mov_b32_e32 v6, v130
	v_fmac_f32_e32 v126, v32, v66
	v_fmac_f32_e32 v127, v32, v94
	v_fmac_f32_e32 v129, v32, v124
	v_fmac_f32_e32 v138, v32, v56
	v_pk_mul_f32 v[20:21], v[134:135], v[24:25]
	v_pk_mul_f32 v[32:33], v[134:135], v[28:29]
	v_pk_mul_f32 v[58:59], v[134:135], v[36:37]
	v_pk_mul_f32 v[96:97], v[134:135], v[44:45]
	v_fmac_f32_e32 v1, v22, v119
	v_fmac_f32_e32 v5, v22, v122
	v_fmac_f32_e32 v100, v22, v62
	v_fmac_f32_e32 v101, v22, v10
	v_mov_b32_e32 v12, v132
	v_mov_b32_e32 v13, v136
	v_fmac_f32_e32 v126, v34, v92
	v_fmac_f32_e32 v127, v34, v98
	v_fmac_f32_e32 v129, v34, v54
	v_fmac_f32_e32 v138, v34, v42
	v_pk_fma_f32 v[20:21], v[6:7], v[8:9], v[20:21]
	v_pk_fma_f32 v[32:33], v[6:7], v[16:17], v[32:33]
	v_pk_fma_f32 v[58:59], v[6:7], v[30:31], v[58:59]
	v_pk_fma_f32 v[6:7], v[6:7], v[40:41], v[96:97]
	v_fmac_f32_e32 v1, v23, v120
	v_fmac_f32_e32 v5, v23, v123
	v_fmac_f32_e32 v100, v23, v63
	v_fmac_f32_e32 v101, v23, v11
	v_mov_b32_e32 v136, v133
	v_fmac_f32_e32 v126, v35, v93
	v_fmac_f32_e32 v127, v35, v99
	v_fmac_f32_e32 v129, v35, v55
	v_fmac_f32_e32 v138, v35, v43
	v_pk_fma_f32 v[20:21], v[12:13], v[26:27], v[20:21]
	v_pk_fma_f32 v[22:23], v[12:13], v[18:19], v[32:33]
	v_pk_fma_f32 v[32:33], v[12:13], v[38:39], v[58:59]
	v_pk_fma_f32 v[6:7], v[12:13], v[46:47], v[6:7]
	v_add_f32_e32 v1, 0, v1
	v_add_f32_e32 v5, 0, v5
	v_add_f32_e32 v34, 0, v100
	v_add_f32_e32 v35, 0, v101
	v_pk_fma_f32 v[12:13], v[136:137], v[48:49], v[20:21]
	v_pk_fma_f32 v[20:21], v[136:137], v[50:51], v[22:23]
	v_pk_fma_f32 v[22:23], v[136:137], v[52:53], v[32:33]
	v_pk_fma_f32 v[6:7], v[136:137], v[14:15], v[6:7]
	v_add_f32_e32 v1, v1, v126
	v_add_f32_e32 v5, v5, v127
	v_add_f32_e32 v32, v34, v129
	v_add_f32_e32 v33, v35, v138
	v_add_f32_e32 v1, v1, v12
	v_add_f32_e32 v5, v5, v20
	v_add_f32_e32 v12, v32, v22
	v_add_f32_e32 v6, v33, v6
	v_add_f32_e32 v1, v1, v13
	v_add_f32_e32 v5, v5, v21
	v_add_f32_e32 v12, v12, v23
	v_add_f32_e32 v6, v6, v7
	v_mov_b32_e32 v236, v1
	v_mov_b32_e32 v237, v5
	v_mov_b32_e32 v238, v12
	v_mov_b32_e32 v239, v6
	s_addk_i32 s14, 0x1010
	v_add_u32_e32 v1, s14, v102
	ds_read_b128 v[20:23], v1
	ds_read_b128 v[32:35], v1 offset:1024
	ds_read_b128 v[130:133], v1 offset:2048
	ds_read_b128 v[134:137], v1 offset:3072
	s_waitcnt lgkmcnt(3)
	v_mul_f32_e32 v1, v21, v118
	v_mul_f32_e32 v5, v21, v121
	v_mul_f32_e32 v100, v21, v61
	v_mul_f32_e32 v101, v21, v65
	s_waitcnt lgkmcnt(2)
	v_mul_f32_e32 v126, v33, v67
	v_mul_f32_e32 v127, v33, v95
	v_mul_f32_e32 v129, v33, v125
	v_mul_f32_e32 v138, v33, v57
	s_waitcnt lgkmcnt(0)
	v_mov_b32_e32 v7, v134
	v_mov_b32_e32 v134, v131
	v_fmac_f32_e32 v1, v20, v117
	v_fmac_f32_e32 v5, v20, v91
	v_fmac_f32_e32 v100, v20, v60
	v_fmac_f32_e32 v101, v20, v64
	v_mov_b32_e32 v6, v130
	v_fmac_f32_e32 v126, v32, v66
	v_fmac_f32_e32 v127, v32, v94
	v_fmac_f32_e32 v129, v32, v124
	v_fmac_f32_e32 v138, v32, v56
	v_pk_mul_f32 v[20:21], v[134:135], v[24:25]
	v_pk_mul_f32 v[32:33], v[134:135], v[28:29]
	v_pk_mul_f32 v[58:59], v[134:135], v[36:37]
	v_pk_mul_f32 v[96:97], v[134:135], v[44:45]
	v_fmac_f32_e32 v1, v22, v119
	v_fmac_f32_e32 v5, v22, v122
	v_fmac_f32_e32 v100, v22, v62
	v_fmac_f32_e32 v101, v22, v10
	v_mov_b32_e32 v12, v132
	v_mov_b32_e32 v13, v136
	v_fmac_f32_e32 v126, v34, v92
	v_fmac_f32_e32 v127, v34, v98
	v_fmac_f32_e32 v129, v34, v54
	v_fmac_f32_e32 v138, v34, v42
	v_pk_fma_f32 v[20:21], v[6:7], v[8:9], v[20:21]
	v_pk_fma_f32 v[32:33], v[6:7], v[16:17], v[32:33]
	v_pk_fma_f32 v[58:59], v[6:7], v[30:31], v[58:59]
	v_pk_fma_f32 v[6:7], v[6:7], v[40:41], v[96:97]
	v_fmac_f32_e32 v1, v23, v120
	v_fmac_f32_e32 v5, v23, v123
	v_fmac_f32_e32 v100, v23, v63
	v_fmac_f32_e32 v101, v23, v11
	v_mov_b32_e32 v136, v133
	v_fmac_f32_e32 v126, v35, v93
	v_fmac_f32_e32 v127, v35, v99
	v_fmac_f32_e32 v129, v35, v55
	v_fmac_f32_e32 v138, v35, v43
	v_pk_fma_f32 v[20:21], v[12:13], v[26:27], v[20:21]
	v_pk_fma_f32 v[22:23], v[12:13], v[18:19], v[32:33]
	v_pk_fma_f32 v[32:33], v[12:13], v[38:39], v[58:59]
	v_pk_fma_f32 v[6:7], v[12:13], v[46:47], v[6:7]
	v_add_f32_e32 v1, 0, v1
	v_add_f32_e32 v5, 0, v5
	v_add_f32_e32 v34, 0, v100
	v_add_f32_e32 v35, 0, v101
	v_pk_fma_f32 v[12:13], v[136:137], v[48:49], v[20:21]
	v_pk_fma_f32 v[20:21], v[136:137], v[50:51], v[22:23]
	v_pk_fma_f32 v[22:23], v[136:137], v[52:53], v[32:33]
	v_pk_fma_f32 v[6:7], v[136:137], v[14:15], v[6:7]
	v_add_f32_e32 v1, v1, v126
	v_add_f32_e32 v5, v5, v127
	v_add_f32_e32 v32, v34, v129
	v_add_f32_e32 v33, v35, v138
	v_add_f32_e32 v1, v1, v12
	v_add_f32_e32 v5, v5, v20
	v_add_f32_e32 v12, v32, v22
	v_add_f32_e32 v6, v33, v6
	v_add_f32_e32 v1, v1, v13
	v_add_f32_e32 v5, v5, v21
	v_add_f32_e32 v12, v12, v23
	v_add_f32_e32 v6, v6, v7
	v_mov_b32_e32 v241, v1
	v_mov_b32_e32 v242, v5
	v_mov_b32_e32 v243, v12
	v_mov_b32_e32 v244, v6
	s_addk_i32 s14, 0x1010
	v_add_u32_e32 v1, s14, v102
	ds_read_b128 v[20:23], v1
	ds_read_b128 v[32:35], v1 offset:1024
	ds_read_b128 v[130:133], v1 offset:2048
	ds_read_b128 v[134:137], v1 offset:3072
	s_waitcnt lgkmcnt(3)
; __global__ void __launch_bounds__(NTHR) fwd_megakernel(Params p) {
;     ...
;       for (int e = 0; e < 16; ++e) {
;         float a4[4] = {0.f, 0.f, 0.f, 0.f};
; #pragma unroll
;         for (int i = 0; i < 4; ++i) {
;           const float4 w = *(const float4*)(wr + e * 1028 + i * 256 + lane * 4);
; #pragma unroll
;           for (int rr = 0; rr < 4; ++rr)
;             a4[rr] += yv[rr][i * 4] * w.x + yv[rr][i * 4 + 1] * w.y + yv[rr][i * 4 + 2] * w.z + yv[rr][i * 4 + 3] * w.w;
;         }
;         float r2[2];
;         { const bool hi = lane & 1;
;           const float s0 = hi ? a4[0] : a4[1], k0 = hi ? a4[1] : a4[0];
;           const float s1 = hi ? a4[2] : a4[3], k1 = hi ? a4[3] : a4[2];
	v_mul_f32_e32 v1, v21, v118
	v_mul_f32_e32 v5, v21, v121
	v_mul_f32_e32 v100, v21, v61
	v_mul_f32_e32 v101, v21, v65
	s_waitcnt lgkmcnt(2)
	v_mul_f32_e32 v126, v33, v67
	v_mul_f32_e32 v127, v33, v95
	v_mul_f32_e32 v129, v33, v125
	v_mul_f32_e32 v138, v33, v57
	s_waitcnt lgkmcnt(0)
	v_mov_b32_e32 v7, v134
	v_mov_b32_e32 v134, v131
	v_fmac_f32_e32 v1, v20, v117
	v_fmac_f32_e32 v5, v20, v91
	v_fmac_f32_e32 v100, v20, v60
	v_fmac_f32_e32 v101, v20, v64
	v_mov_b32_e32 v6, v130
	v_fmac_f32_e32 v126, v32, v66
	v_fmac_f32_e32 v127, v32, v94
	v_fmac_f32_e32 v129, v32, v124
	v_fmac_f32_e32 v138, v32, v56
	v_pk_mul_f32 v[20:21], v[134:135], v[24:25]
	v_pk_mul_f32 v[32:33], v[134:135], v[28:29]
	v_pk_mul_f32 v[58:59], v[134:135], v[36:37]
	v_pk_mul_f32 v[96:97], v[134:135], v[44:45]
	v_fmac_f32_e32 v1, v22, v119
	v_fmac_f32_e32 v5, v22, v122
	v_fmac_f32_e32 v100, v22, v62
	v_fmac_f32_e32 v101, v22, v10
	v_mov_b32_e32 v12, v132
	v_mov_b32_e32 v13, v136
	v_fmac_f32_e32 v126, v34, v92
	v_fmac_f32_e32 v127, v34, v98
	v_fmac_f32_e32 v129, v34, v54
	v_fmac_f32_e32 v138, v34, v42
	v_pk_fma_f32 v[20:21], v[6:7], v[8:9], v[20:21]
	v_pk_fma_f32 v[32:33], v[6:7], v[16:17], v[32:33]
	v_pk_fma_f32 v[58:59], v[6:7], v[30:31], v[58:59]
	v_pk_fma_f32 v[6:7], v[6:7], v[40:41], v[96:97]
	v_fmac_f32_e32 v1, v23, v120
	v_fmac_f32_e32 v5, v23, v123
	v_fmac_f32_e32 v100, v23, v63
	v_fmac_f32_e32 v101, v23, v11
	v_mov_b32_e32 v136, v133
	v_fmac_f32_e32 v126, v35, v93
	v_fmac_f32_e32 v127, v35, v99
	v_fmac_f32_e32 v129, v35, v55
	v_fmac_f32_e32 v138, v35, v43
	v_pk_fma_f32 v[20:21], v[12:13], v[26:27], v[20:21]
	v_pk_fma_f32 v[22:23], v[12:13], v[18:19], v[32:33]
	v_pk_fma_f32 v[32:33], v[12:13], v[38:39], v[58:59]
	v_pk_fma_f32 v[6:7], v[12:13], v[46:47], v[6:7]
	v_add_f32_e32 v1, 0, v1
	v_add_f32_e32 v5, 0, v5
	v_add_f32_e32 v34, 0, v100
	v_add_f32_e32 v35, 0, v101
	v_pk_fma_f32 v[12:13], v[136:137], v[48:49], v[20:21]
	v_pk_fma_f32 v[20:21], v[136:137], v[50:51], v[22:23]
	v_pk_fma_f32 v[22:23], v[136:137], v[52:53], v[32:33]
	v_pk_fma_f32 v[6:7], v[136:137], v[14:15], v[6:7]
	v_add_f32_e32 v1, v1, v126
	v_add_f32_e32 v5, v5, v127
	v_add_f32_e32 v32, v34, v129
	v_add_f32_e32 v33, v35, v138
	v_add_f32_e32 v1, v1, v12
	v_add_f32_e32 v5, v5, v20
	v_add_f32_e32 v12, v32, v22
	v_add_f32_e32 v6, v33, v6
	v_add_f32_e32 v1, v1, v13
	v_add_f32_e32 v5, v5, v21
	v_add_f32_e32 v12, v12, v23
	v_add_f32_e32 v6, v6, v7
	v_mov_b32_e32 v246, v1
	v_mov_b32_e32 v247, v5
	v_mov_b32_e32 v248, v12
	v_mov_b32_e32 v249, v6
	s_addk_i32 s14, 0x1010
	v_add_u32_e32 v1, s14, v102
	ds_read_b128 v[20:23], v1
	ds_read_b128 v[32:35], v1 offset:1024
	ds_read_b128 v[130:133], v1 offset:2048
	ds_read_b128 v[134:137], v1 offset:3072
	s_waitcnt lgkmcnt(3)
	v_mul_f32_e32 v1, v21, v118
	v_mul_f32_e32 v5, v21, v121
	v_mul_f32_e32 v100, v21, v61
	v_mul_f32_e32 v101, v21, v65
	s_waitcnt lgkmcnt(2)
	v_mul_f32_e32 v126, v33, v67
	v_mul_f32_e32 v127, v33, v95
	v_mul_f32_e32 v129, v33, v125
	v_mul_f32_e32 v138, v33, v57
	s_waitcnt lgkmcnt(0)
	v_mov_b32_e32 v7, v134
	v_mov_b32_e32 v134, v131
	v_fmac_f32_e32 v1, v20, v117
	v_fmac_f32_e32 v5, v20, v91
	v_fmac_f32_e32 v100, v20, v60
	v_fmac_f32_e32 v101, v20, v64
	v_mov_b32_e32 v6, v130
	v_fmac_f32_e32 v126, v32, v66
	v_fmac_f32_e32 v127, v32, v94
	v_fmac_f32_e32 v129, v32, v124
	v_fmac_f32_e32 v138, v32, v56
	v_pk_mul_f32 v[20:21], v[134:135], v[24:25]
	v_pk_mul_f32 v[32:33], v[134:135], v[28:29]
	v_pk_mul_f32 v[58:59], v[134:135], v[36:37]
	v_pk_mul_f32 v[96:97], v[134:135], v[44:45]
	v_fmac_f32_e32 v1, v22, v119
	v_fmac_f32_e32 v5, v22, v122
	v_fmac_f32_e32 v100, v22, v62
	v_fmac_f32_e32 v101, v22, v10
	v_mov_b32_e32 v12, v132
	v_mov_b32_e32 v13, v136
	v_fmac_f32_e32 v126, v34, v92
	v_fmac_f32_e32 v127, v34, v98
	v_fmac_f32_e32 v129, v34, v54
	v_fmac_f32_e32 v138, v34, v42
	v_pk_fma_f32 v[20:21], v[6:7], v[8:9], v[20:21]
	v_pk_fma_f32 v[32:33], v[6:7], v[16:17], v[32:33]
	v_pk_fma_f32 v[58:59], v[6:7], v[30:31], v[58:59]
	v_pk_fma_f32 v[6:7], v[6:7], v[40:41], v[96:97]
	v_fmac_f32_e32 v1, v23, v120
	v_fmac_f32_e32 v5, v23, v123
	v_fmac_f32_e32 v100, v23, v63
	v_fmac_f32_e32 v101, v23, v11
	v_mov_b32_e32 v136, v133
	v_fmac_f32_e32 v126, v35, v93
	v_fmac_f32_e32 v127, v35, v99
	v_fmac_f32_e32 v129, v35, v55
	v_fmac_f32_e32 v138, v35, v43
	v_pk_fma_f32 v[20:21], v[12:13], v[26:27], v[20:21]
	v_pk_fma_f32 v[22:23], v[12:13], v[18:19], v[32:33]
	v_pk_fma_f32 v[32:33], v[12:13], v[38:39], v[58:59]
	v_pk_fma_f32 v[6:7], v[12:13], v[46:47], v[6:7]
	v_add_f32_e32 v1, 0, v1
	v_add_f32_e32 v5, 0, v5
	v_add_f32_e32 v34, 0, v100
	v_add_f32_e32 v35, 0, v101
	v_pk_fma_f32 v[12:13], v[136:137], v[48:49], v[20:21]
	v_pk_fma_f32 v[20:21], v[136:137], v[50:51], v[22:23]
	v_pk_fma_f32 v[22:23], v[136:137], v[52:53], v[32:33]
	v_pk_fma_f32 v[6:7], v[136:137], v[14:15], v[6:7]
	v_add_f32_e32 v1, v1, v126
	v_add_f32_e32 v5, v5, v127
	v_add_f32_e32 v32, v34, v129
	v_add_f32_e32 v33, v35, v138
	v_add_f32_e32 v1, v1, v12
	v_add_f32_e32 v5, v5, v20
	v_add_f32_e32 v12, v32, v22
	v_add_f32_e32 v6, v33, v6
	v_add_f32_e32 v1, v1, v13
	v_add_f32_e32 v5, v5, v21
	v_add_f32_e32 v12, v12, v23
	v_add_f32_e32 v6, v6, v7
	v_mov_b32_e32 v251, v1
	v_mov_b32_e32 v252, v5
	v_mov_b32_e32 v253, v12
	v_mov_b32_e32 v254, v6
	s_addk_i32 s14, 0x1010
	v_cndmask_b32_e64 v240, v236, v237, s[10:11]
	v_cndmask_b32_e64 v236, v237, v236, s[10:11]
	v_cndmask_b32_e64 v237, v238, v239, s[10:11]
	v_cndmask_b32_e64 v239, v239, v238, s[10:11]
	v_cndmask_b32_e64 v245, v241, v242, s[10:11]
	v_cndmask_b32_e64 v241, v242, v241, s[10:11]
	v_cndmask_b32_e64 v242, v243, v244, s[10:11]
	v_cndmask_b32_e64 v244, v244, v243, s[10:11]
; __global__ void __launch_bounds__(NTHR) fwd_megakernel(Params p) {
;     ...
;         float r2[2];
;         { const bool hi = lane & 1;
;           const float s0 = hi ? a4[0] : a4[1], k0 = hi ? a4[1] : a4[0];
;           const float s1 = hi ? a4[2] : a4[3], k1 = hi ? a4[3] : a4[2];
;           r2[0] = k0 + __shfl_xor(s0, 1); r2[1] = k1 + __shfl_xor(s1, 1); }
;         float r1;
;         { const bool hi = lane & 2;
;           const float s0 = hi ? r2[0] : r2[1], k0 = hi ? r2[1] : r2[0];
;           r1 = k0 + __shfl_xor(s0, 2); }
;         r1 += __shfl_xor(r1, 4); r1 += __shfl_xor(r1, 8); r1 += __shfl_xor(r1, 16); r1 += __shfl_xor(r1, 32);
; #pragma unroll
;         for (int rr = 0; rr < 4; ++rr) {
;           const float val = __shfl(r1, rr);
;           if (lane == e) mine[rr] = val;
;         }
;       }
; #pragma unroll
;       for (int rr = 0; rr < 4; ++rr) {
;         float lgv = (lane < 16) ? mine[rr] : -INFINITY;
;         float mxv = lgv;
; #pragma unroll
;         for (int o = 8; o > 0; o >>= 1) mxv = fmaxf(mxv, __shfl_xor(mxv, o));
;         mxv = __shfl(mxv, 0);
;         const float ex = (lane < 16) ? expf(lgv - mxv) : 0.f;
;         float den = ex;
; #pragma unroll
;         for (int o = 8; o > 0; o >>= 1) den += __shfl_xor(den, o);
;         den = __shfl(den, 0);
;         const int t = (row0 + rr) & 2047;
;         if (lane < 16) aff[((size_t)(b * 16 + lane)) * 2048 + t] = ex / den;
	v_cndmask_b32_e64 v250, v246, v247, s[10:11]
	v_cndmask_b32_e64 v246, v247, v246, s[10:11]
	v_cndmask_b32_e64 v247, v248, v249, s[10:11]
	v_cndmask_b32_e64 v249, v249, v248, s[10:11]
	v_cndmask_b32_e64 v255, v251, v252, s[10:11]
	v_cndmask_b32_e64 v251, v252, v251, s[10:11]
	v_cndmask_b32_e64 v252, v253, v254, s[10:11]
	v_cndmask_b32_e64 v254, v254, v253, s[10:11]
	s_nop 1
	v_add_f32_dpp v236, v240, v236 quad_perm:[1,0,3,2] row_mask:0xf bank_mask:0xf
	v_add_f32_dpp v237, v237, v239 quad_perm:[1,0,3,2] row_mask:0xf bank_mask:0xf
	v_add_f32_dpp v241, v245, v241 quad_perm:[1,0,3,2] row_mask:0xf bank_mask:0xf
	v_add_f32_dpp v242, v242, v244 quad_perm:[1,0,3,2] row_mask:0xf bank_mask:0xf
	v_add_f32_dpp v246, v250, v246 quad_perm:[1,0,3,2] row_mask:0xf bank_mask:0xf
	v_add_f32_dpp v247, v247, v249 quad_perm:[1,0,3,2] row_mask:0xf bank_mask:0xf
	v_add_f32_dpp v251, v255, v251 quad_perm:[1,0,3,2] row_mask:0xf bank_mask:0xf
	v_add_f32_dpp v252, v252, v254 quad_perm:[1,0,3,2] row_mask:0xf bank_mask:0xf
	v_cndmask_b32_e64 v239, v236, v237, s[12:13]
	v_cndmask_b32_e64 v236, v237, v236, s[12:13]
	v_cndmask_b32_e64 v244, v241, v242, s[12:13]
	v_cndmask_b32_e64 v241, v242, v241, s[12:13]
	v_cndmask_b32_e64 v249, v246, v247, s[12:13]
	v_cndmask_b32_e64 v246, v247, v246, s[12:13]
	v_cndmask_b32_e64 v254, v251, v252, s[12:13]
	v_cndmask_b32_e64 v251, v252, v251, s[12:13]
	s_nop 1
	v_add_f32_dpp v236, v239, v236 quad_perm:[2,3,0,1] row_mask:0xf bank_mask:0xf
	v_add_f32_dpp v241, v244, v241 quad_perm:[2,3,0,1] row_mask:0xf bank_mask:0xf
	v_add_f32_dpp v246, v249, v246 quad_perm:[2,3,0,1] row_mask:0xf bank_mask:0xf
	v_add_f32_dpp v251, v254, v251 quad_perm:[2,3,0,1] row_mask:0xf bank_mask:0xf
	s_nop 1
	ds_bpermute_b32 v237, v106, v236
	ds_bpermute_b32 v242, v106, v241
	ds_bpermute_b32 v247, v106, v246
	ds_bpermute_b32 v252, v106, v251
	s_waitcnt lgkmcnt(0)
	v_add_f32_e32 v236, v236, v237
	v_add_f32_e32 v241, v241, v242
	v_add_f32_e32 v246, v246, v247
	v_add_f32_e32 v251, v251, v252
	ds_bpermute_b32 v237, v105, v236
	ds_bpermute_b32 v242, v105, v241
	ds_bpermute_b32 v247, v105, v246
	ds_bpermute_b32 v252, v105, v251
	s_waitcnt lgkmcnt(0)
	v_add_f32_e32 v236, v236, v237
	v_add_f32_e32 v241, v241, v242
	v_add_f32_e32 v246, v246, v247
	v_add_f32_e32 v251, v251, v252
	v_mov_b32_e32 v237, v236
	v_mov_b32_e32 v242, v241
	v_mov_b32_e32 v247, v246
	v_mov_b32_e32 v252, v251
	s_nop 1
	v_permlane16_swap_b32_e32 v237, v236
	v_permlane16_swap_b32_e32 v242, v241
	v_permlane16_swap_b32_e32 v247, v246
	v_permlane16_swap_b32_e32 v252, v251
	s_nop 1
	v_add_f32_e32 v236, v237, v236
	v_add_f32_e32 v241, v242, v241
	v_add_f32_e32 v246, v247, v246
	v_add_f32_e32 v251, v252, v251
	v_mov_b32_e32 v237, v236
	v_mov_b32_e32 v242, v241
	v_mov_b32_e32 v247, v246
	v_mov_b32_e32 v252, v251
	s_nop 1
	v_permlane32_swap_b32_e32 v237, v236
	v_permlane32_swap_b32_e32 v242, v241
	v_permlane32_swap_b32_e32 v247, v246
	v_permlane32_swap_b32_e32 v252, v251
	s_nop 1
	v_add_f32_e32 v236, v237, v236
	v_add_f32_e32 v241, v242, v241
	v_add_f32_e32 v246, v247, v246
	v_add_f32_e32 v251, v252, v251
	ds_bpermute_b32 v237, v109, v236
	ds_bpermute_b32 v239, v110, v236
	ds_bpermute_b32 v240, v111, v236
	ds_bpermute_b32 v238, v112, v236
	ds_bpermute_b32 v242, v109, v241
	ds_bpermute_b32 v244, v110, v241
	ds_bpermute_b32 v245, v111, v241
	ds_bpermute_b32 v243, v112, v241
	ds_bpermute_b32 v247, v109, v246
	ds_bpermute_b32 v249, v110, v246
	ds_bpermute_b32 v250, v111, v246
	ds_bpermute_b32 v248, v112, v246
	ds_bpermute_b32 v252, v109, v251
	ds_bpermute_b32 v254, v110, v251
	ds_bpermute_b32 v255, v111, v251
	ds_bpermute_b32 v253, v112, v251
	s_waitcnt lgkmcnt(0)
	s_add_i32 s99, s14, 0xffffbfc0
	v_cmp_eq_u32_e32 vcc, s99, v114
	s_nop 1
	v_cndmask_b32_e32 v0, v0, v237, vcc
	v_cndmask_b32_e32 v4, v4, v239, vcc
	v_cndmask_b32_e32 v3, v3, v240, vcc
	v_cndmask_b32_e32 v2, v2, v238, vcc
	s_add_i32 s99, s14, 0xffffcfd0
	v_cmp_eq_u32_e32 vcc, s99, v114
	s_nop 1
	v_cndmask_b32_e32 v0, v0, v242, vcc
	v_cndmask_b32_e32 v4, v4, v244, vcc
	v_cndmask_b32_e32 v3, v3, v245, vcc
	v_cndmask_b32_e32 v2, v2, v243, vcc
	s_add_i32 s99, s14, 0xffffdfe0
	v_cmp_eq_u32_e32 vcc, s99, v114
	s_nop 1
	v_cndmask_b32_e32 v0, v0, v247, vcc
	v_cndmask_b32_e32 v4, v4, v249, vcc
	v_cndmask_b32_e32 v3, v3, v250, vcc
	v_cndmask_b32_e32 v2, v2, v248, vcc
	s_add_i32 s99, s14, 0xffffeff0
	v_cmp_eq_u32_e32 vcc, s99, v114
	s_nop 1
	v_cndmask_b32_e32 v0, v0, v252, vcc
	v_cndmask_b32_e32 v4, v4, v254, vcc
	v_cndmask_b32_e32 v3, v3, v255, vcc
	v_cndmask_b32_e32 v2, v2, v253, vcc
	s_cmp_eq_u32 s14, 0x10100
	s_cbranch_scc0 .Lrt_loop
	v_cndmask_b32_e64 v0, v115, v0, s[6:7]
	ds_bpermute_b32 v1, v105, v0
	v_max_f32_e32 v5, v0, v0
	v_and_b32_e32 v7, 0x7fc, v90
	s_waitcnt lgkmcnt(0)
	v_max_f32_e32 v1, v1, v1
	v_max_f32_e32 v1, v5, v1
	ds_bpermute_b32 v5, v106, v1
	s_waitcnt lgkmcnt(0)
	v_max_f32_e32 v5, v5, v5
	v_max_f32_e32 v1, v1, v5
	ds_bpermute_b32 v5, v107, v1
	s_waitcnt lgkmcnt(0)
	v_max_f32_e32 v5, v5, v5
	v_max_f32_e32 v1, v1, v5
	ds_bpermute_b32 v5, v108, v1
	s_waitcnt lgkmcnt(0)
	v_max_f32_e32 v5, v5, v5
	v_max_f32_e32 v1, v1, v5
	ds_bpermute_b32 v1, v113, v1
	s_waitcnt lgkmcnt(0)
	v_sub_f32_e32 v0, v0, v1
	v_mul_f32_e32 v1, 0x3fb8aa3b, v0
	v_fma_f32 v5, v0, s27, -v1
	v_rndne_f32_e32 v6, v1
	v_fmac_f32_e32 v5, 0x32a5705f, v0
	v_sub_f32_e32 v1, v1, v6
	v_add_f32_e32 v1, v1, v5
	v_cvt_i32_f32_e32 v6, v6
	v_exp_f32_e32 v1, v1
	v_cmp_ngt_f32_e32 vcc, s30, v0
	v_ldexp_f32 v1, v1, v6
	s_nop 0
	v_cndmask_b32_e32 v1, 0, v1, vcc
	v_cmp_nlt_f32_e32 vcc, s31, v0
	s_nop 1
	v_cndmask_b32_e32 v5, v116, v1, vcc
	v_cndmask_b32_e64 v0, 0, v5, s[6:7]
	ds_bpermute_b32 v1, v105, v0
	s_waitcnt lgkmcnt(0)
	v_add_f32_e32 v0, v0, v1
	ds_bpermute_b32 v1, v106, v0
	s_waitcnt lgkmcnt(0)
	v_add_f32_e32 v0, v0, v1
	ds_bpermute_b32 v1, v107, v0
	s_waitcnt lgkmcnt(0)
	v_add_f32_e32 v1, v0, v1
	ds_bpermute_b32 v6, v108, v1
	v_lshl_add_u32 v0, v68, 4, v196
	v_lshlrev_b32_e32 v68, 2, v7
	s_waitcnt lgkmcnt(0)
	v_add_f32_e32 v1, v1, v6
	ds_bpermute_b32 v6, v113, v1
	v_ashrrev_i32_e32 v1, 31, v0
	v_lshlrev_b64 v[0:1], 13, v[0:1]
	v_lshl_add_u64 v[0:1], s[18:19], 0, v[0:1]
	s_and_saveexec_b64 s[14:15], s[6:7]
	s_cbranch_execz .LBB0_1026
	s_waitcnt lgkmcnt(0)
	v_div_scale_f32 v7, s[16:17], v6, v6, v5
	v_rcp_f32_e32 v8, v7
	v_div_scale_f32 v9, vcc, v5, v6, v5
	v_fma_f32 v10, -v7, v8, 1.0
	v_fmac_f32_e32 v8, v10, v8
	v_mul_f32_e32 v10, v9, v8
	v_fma_f32 v11, -v7, v10, v9
	v_fmac_f32_e32 v10, v11, v8
	v_fma_f32 v7, -v7, v10, v9
	v_div_fmas_f32 v7, v7, v8, v10
	v_div_fixup_f32 v5, v7, v6, v5
	v_lshl_add_u64 v[6:7], v[0:1], 0, v[68:69]
	global_store_dword v[6:7], v5, off
